# conv unit: the 32 depthwise-weight loads issued before the fill phase so their latency overlaps the a/gate row loads (on top of v42)
# speedup vs baseline: 1.0003x; 1.0003x over previous
; #define LAS __attribute__((address_space(3)))
; __device__ __forceinline__ float sigmoidf_(float x) { return __builtin_amdgcn_rcpf(1.0f + __builtin_amdgcn_exp2f(-x * LOG2E)); }
; __device__ __forceinline__ void conv_unit(const Ctx& C0, const Params& p, int l, int unit) {
;     const Ctx C = relaunder(C0);
;     LAS float* U = (LAS float*)C.lds;
;     const int c = C.tid, t0 = unit * 32, s0 = t0 & (SEQ - 1);
;     const bf16* P = (const bf16*)(p.ws + WS_P);
;     { const int cg8 = (c & 63) * 8, rsub = c >> 6;
; #pragma unroll
;       for (int pass = 0; pass < 8; ++pass) {
;         const int r = pass * 8 + rsub;
;         if (r < 62) {
;             const int s = s0 - 30 + r; f32x4 u0 = (f32x4){0.f, 0.f, 0.f, 0.f}, u1 = u0;
;             if (s >= 0) { const bf16* row = P + (size_t)(t0 - 30 + r) * PN + C_UB + cg8; const v4u a = *(const v4u*)row, g = *(const v4u*)(row + 512);
;                 u0[0] = bflo(a.x) * sigmoidf_(bflo(g.x)); u0[1] = bfhi(a.x) * sigmoidf_(bfhi(g.x)); u0[2] = bflo(a.y) * sigmoidf_(bflo(g.y)); u0[3] = bfhi(a.y) * sigmoidf_(bfhi(g.y));
;                 u1[0] = bflo(a.z) * sigmoidf_(bflo(g.z)); u1[1] = bfhi(a.z) * sigmoidf_(bfhi(g.z)); u1[2] = bflo(a.w) * sigmoidf_(bflo(g.w)); u1[3] = bfhi(a.w) * sigmoidf_(bfhi(g.w)); }
;             *(LAS f32x4*)(U + r * 512 + cg8) = u0; *(LAS f32x4*)(U + r * 512 + cg8 + 4) = u1;
;         }
;       }
;     }
;     __syncthreads();
;     float w[31];
; #pragma unroll
;     for (int j = 0; j < 31; ++j) w[j] = p.w_dw[(size_t)l * 31 * 512 + j * 512 + c];
;     const float bias = p.b_dw[l * 512 + c];
.LBB0_280:
	v_mov_b32_e32 v10, v185
	s_lshl_b32 s0, s37, 5
	v_lshlrev_b32_e32 v0, 3, v10
	s_and_b32 s1, s0, 0xfe0
	v_and_b32_e32 v12, 0x1f8, v0
	v_ashrrev_i32_e32 v13, 6, v10
	v_lshl_add_u32 v11, v12, 2, 0
	s_sub_i32 s9, 29, s1
	s_sub_i32 s8, s0, 30
	v_readfirstlane_b32 s4, v13
	v_lshlrev_b32_e32 v120, 1, v12
	v_lshl_add_u32 v121, v13, 11, v11
	v_add_u32_e32 v122, 0x10000, v121
	v_ashrrev_i32_e32 v11, 31, v10
	s_waitcnt vmcnt(6)
	v_lshl_add_u64 v[4:5], v[10:11], 2, s[38:39]
	v_add_co_u32_e32 v64, vcc, 0xf000, v4
	s_mov_b32 s0, 0xe000
	s_nop 0
	v_addc_co_u32_e32 v65, vcc, 0, v5, vcc
	v_add_co_u32_e32 v62, vcc, s0, v4
	s_mov_b32 s0, 0xc000
	s_nop 0
	v_addc_co_u32_e32 v63, vcc, 0, v5, vcc
	v_add_co_u32_e32 v58, vcc, 0xd000, v4
	v_add_u32_e32 v2, s88, v10
	s_nop 0
	v_addc_co_u32_e32 v59, vcc, 0, v5, vcc
	v_add_co_u32_e32 v54, vcc, s0, v4
	s_mov_b32 s0, 0xa000
	s_nop 0
	v_addc_co_u32_e32 v55, vcc, 0, v5, vcc
	v_add_co_u32_e32 v50, vcc, 0xb000, v4
	v_readlane_b32 s44, v251, 12
	s_nop 0
	v_addc_co_u32_e32 v51, vcc, 0, v5, vcc
	v_add_co_u32_e32 v46, vcc, s0, v4
	s_mov_b32 s0, 0x8000
	s_nop 0
	v_addc_co_u32_e32 v47, vcc, 0, v5, vcc
	v_add_co_u32_e32 v42, vcc, 0x9000, v4
	v_ashrrev_i32_e32 v3, 31, v2
	s_nop 0
	v_addc_co_u32_e32 v43, vcc, 0, v5, vcc
	s_waitcnt vmcnt(3)
	v_add_co_u32_e32 v38, vcc, s0, v4
	s_movk_i32 s0, 0x6000
	s_waitcnt vmcnt(2)
	v_addc_co_u32_e32 v39, vcc, 0, v5, vcc
	v_add_co_u32_e32 v34, vcc, 0x7000, v4
	v_readlane_b32 s52, v251, 20
	s_nop 0
	v_addc_co_u32_e32 v35, vcc, 0, v5, vcc
	v_add_co_u32_e32 v30, vcc, s0, v4
	s_movk_i32 s0, 0x4000
	s_nop 0
	v_addc_co_u32_e32 v31, vcc, 0, v5, vcc
	v_add_co_u32_e32 v26, vcc, 0x5000, v4
	v_readlane_b32 s53, v251, 21
	s_nop 0
	v_addc_co_u32_e32 v27, vcc, 0, v5, vcc
	v_add_co_u32_e32 v22, vcc, s0, v4
	s_movk_i32 s0, 0x3000
	s_nop 0
	v_addc_co_u32_e32 v23, vcc, 0, v5, vcc
	v_add_co_u32_e32 v18, vcc, s0, v4
	s_movk_i32 s0, 0x2000
	s_nop 0
	v_addc_co_u32_e32 v19, vcc, 0, v5, vcc
	v_add_co_u32_e32 v14, vcc, s0, v4
	s_movk_i32 s0, 0x1000
	s_nop 0
	v_addc_co_u32_e32 v15, vcc, 0, v5, vcc
	v_lshl_add_u64 v[66:67], v[2:3], 2, s[52:53]
	v_add_co_u32_e32 v8, vcc, s0, v4
	v_addc_co_u32_e32 v9, vcc, 0, v5, vcc
	global_load_dword v2, v[4:5], off
	s_nop 0
	global_load_dword v4, v[4:5], off offset:2048
	s_nop 0
	global_load_dword v6, v[8:9], off
	s_nop 0
	global_load_dword v8, v[8:9], off offset:2048
	s_nop 0
	global_load_dword v12, v[14:15], off
	s_nop 0
	global_load_dword v14, v[14:15], off offset:2048
	s_nop 0
	global_load_dword v16, v[18:19], off
	s_nop 0
	global_load_dword v18, v[18:19], off offset:2048
	s_nop 0
	global_load_dword v20, v[22:23], off
	s_nop 0
	global_load_dword v22, v[22:23], off offset:2048
	s_nop 0
	global_load_dword v24, v[26:27], off
	s_nop 0
	global_load_dword v26, v[26:27], off offset:2048
	s_nop 0
	global_load_dword v28, v[30:31], off
	s_nop 0
	global_load_dword v30, v[30:31], off offset:2048
	s_nop 0
	global_load_dword v32, v[34:35], off
	s_nop 0
	global_load_dword v34, v[34:35], off offset:2048
	s_nop 0
	global_load_dword v36, v[38:39], off
	s_nop 0
	global_load_dword v38, v[38:39], off offset:2048
	s_nop 0
	global_load_dword v40, v[42:43], off
	s_nop 0
	global_load_dword v42, v[42:43], off offset:2048
	s_nop 0
	global_load_dword v44, v[46:47], off
	s_nop 0
	global_load_dword v46, v[46:47], off offset:2048
	s_nop 0
	global_load_dword v48, v[50:51], off
	s_nop 0
	global_load_dword v50, v[50:51], off offset:2048
	s_nop 0
	global_load_dword v52, v[54:55], off
	s_nop 0
	global_load_dword v54, v[54:55], off offset:2048
	s_nop 0
	global_load_dword v56, v[58:59], off
	s_nop 0
	global_load_dword v58, v[58:59], off offset:2048
	s_nop 0
	global_load_dword v60, v[62:63], off
	s_nop 0
	global_load_dword v62, v[62:63], off offset:2048
	s_nop 0
	global_load_dword v64, v[64:65], off
	s_nop 0
	global_load_dword v66, v[66:67], off
	s_add_i32 s1, s4, 0
	s_cmp_gt_i32 s1, s9
	s_cbranch_scc0 .Lcf_zero0
	s_add_i32 s10, s8, s1
	s_mul_i32 s10, s10, s86
	s_add_u32 s12, s18, s10
	s_addc_u32 s13, s19, 0
	s_add_u32 s12, s12, 0x6900600
	s_addc_u32 s13, s13, 0
	global_load_dwordx4 v[198:201], v120, s[12:13]
	global_load_dwordx4 v[202:205], v120, s[12:13] offset:1024
	s_branch .Lcf_next0
; __device__ __forceinline__ void conv_unit(const Ctx& C0, const Params& p, int l, int unit) {
;     ...
;     { const int cg8 = (c & 63) * 8, rsub = c >> 6;
; #pragma unroll
;       for (int pass = 0; pass < 8; ++pass) {
;         const int r = pass * 8 + rsub;
;         if (r < 62) {
;             const int s = s0 - 30 + r; f32x4 u0 = (f32x4){0.f, 0.f, 0.f, 0.f}, u1 = u0;
;             if (s >= 0) { const bf16* row = P + (size_t)(t0 - 30 + r) * PN + C_UB + cg8; const v4u a = *(const v4u*)row, g = *(const v4u*)(row + 512);
.Lcf_zero0:
	v_mov_b32_e32 v198, 0
	v_mov_b32_e32 v199, 0
	v_mov_b32_e32 v200, 0
	v_mov_b32_e32 v201, 0
	v_mov_b32_e32 v202, 0
	v_mov_b32_e32 v203, 0
	v_mov_b32_e32 v204, 0
	v_mov_b32_e32 v205, 0
.Lcf_next0:
	s_add_i32 s1, s4, 8
	s_cmp_gt_i32 s1, s9
	s_cbranch_scc0 .Lcf_zero1
	s_add_i32 s10, s8, s1
	s_mul_i32 s10, s10, s86
	s_add_u32 s20, s18, s10
	s_addc_u32 s21, s19, 0
	s_add_u32 s20, s20, 0x6900600
	s_addc_u32 s21, s21, 0
	global_load_dwordx4 v[206:209], v120, s[20:21]
	global_load_dwordx4 v[210:213], v120, s[20:21] offset:1024
	s_branch .Lcf_next1
.Lcf_zero1:
	v_mov_b32_e32 v206, 0
	v_mov_b32_e32 v207, 0
	v_mov_b32_e32 v208, 0
	v_mov_b32_e32 v209, 0
	v_mov_b32_e32 v210, 0
	v_mov_b32_e32 v211, 0
	v_mov_b32_e32 v212, 0
	v_mov_b32_e32 v213, 0
.Lcf_next1:
	s_add_i32 s1, s4, 16
	s_cmp_gt_i32 s1, s9
	s_cbranch_scc0 .Lcf_zero2
	s_add_i32 s10, s8, s1
	s_mul_i32 s10, s10, s86
	s_add_u32 s12, s18, s10
	s_addc_u32 s13, s19, 0
	s_add_u32 s12, s12, 0x6900600
	s_addc_u32 s13, s13, 0
	global_load_dwordx4 v[214:217], v120, s[12:13]
	global_load_dwordx4 v[218:221], v120, s[12:13] offset:1024
	s_branch .Lcf_next2
.Lcf_zero2:
	v_mov_b32_e32 v214, 0
	v_mov_b32_e32 v215, 0
	v_mov_b32_e32 v216, 0
	v_mov_b32_e32 v217, 0
	v_mov_b32_e32 v218, 0
	v_mov_b32_e32 v219, 0
	v_mov_b32_e32 v220, 0
	v_mov_b32_e32 v221, 0
.Lcf_next2:
	s_add_i32 s1, s4, 24
	s_cmp_gt_i32 s1, s9
	s_cbranch_scc0 .Lcf_zero3
	s_add_i32 s10, s8, s1
	s_mul_i32 s10, s10, s86
	s_add_u32 s20, s18, s10
	s_addc_u32 s21, s19, 0
	s_add_u32 s20, s20, 0x6900600
	s_addc_u32 s21, s21, 0
	global_load_dwordx4 v[222:225], v120, s[20:21]
	global_load_dwordx4 v[226:229], v120, s[20:21] offset:1024
	s_branch .Lcf_next3
.Lcf_zero3:
	v_mov_b32_e32 v222, 0
	v_mov_b32_e32 v223, 0
	v_mov_b32_e32 v224, 0
	v_mov_b32_e32 v225, 0
	v_mov_b32_e32 v226, 0
	v_mov_b32_e32 v227, 0
	v_mov_b32_e32 v228, 0
	v_mov_b32_e32 v229, 0
.Lcf_next3:
	s_add_i32 s1, s4, 32
	s_cmp_gt_i32 s1, s9
	s_cbranch_scc0 .Lcf_zero4
	s_add_i32 s10, s8, s1
	s_mul_i32 s10, s10, s86
	s_add_u32 s12, s18, s10
	s_addc_u32 s13, s19, 0
	s_add_u32 s12, s12, 0x6900600
	s_addc_u32 s13, s13, 0
	global_load_dwordx4 v[230:233], v120, s[12:13]
	global_load_dwordx4 v[234:237], v120, s[12:13] offset:1024
	s_branch .Lcf_next4
.Lcf_zero4:
	v_mov_b32_e32 v230, 0
	v_mov_b32_e32 v231, 0
	v_mov_b32_e32 v232, 0
	v_mov_b32_e32 v233, 0
	v_mov_b32_e32 v234, 0
	v_mov_b32_e32 v235, 0
	v_mov_b32_e32 v236, 0
	v_mov_b32_e32 v237, 0
.Lcf_next4:
	s_add_i32 s1, s4, 40
	s_cmp_gt_i32 s1, s9
	s_cbranch_scc0 .Lcf_zero5
	s_add_i32 s10, s8, s1
	s_mul_i32 s10, s10, s86
	s_add_u32 s20, s18, s10
	s_addc_u32 s21, s19, 0
	s_add_u32 s20, s20, 0x6900600
	s_addc_u32 s21, s21, 0
	global_load_dwordx4 v[238:241], v120, s[20:21]
	global_load_dwordx4 v[242:245], v120, s[20:21] offset:1024
	s_branch .Lcf_next5
.Lcf_zero5:
	v_mov_b32_e32 v238, 0
	v_mov_b32_e32 v239, 0
	v_mov_b32_e32 v240, 0
	v_mov_b32_e32 v241, 0
	v_mov_b32_e32 v242, 0
	v_mov_b32_e32 v243, 0
	v_mov_b32_e32 v244, 0
	v_mov_b32_e32 v245, 0
.Lcf_next5:
	s_add_i32 s1, s4, 48
	s_cmp_gt_i32 s1, s9
	s_cbranch_scc0 .Lcf_zero6
	s_add_i32 s10, s8, s1
	s_mul_i32 s10, s10, s86
	s_add_u32 s12, s18, s10
	s_addc_u32 s13, s19, 0
	s_add_u32 s12, s12, 0x6900600
	s_addc_u32 s13, s13, 0
	global_load_dwordx4 v[246:249], v120, s[12:13]
	global_load_dwordx4 v[68:71], v120, s[12:13] offset:1024
	s_branch .Lcf_next6
.Lcf_zero6:
	v_mov_b32_e32 v246, 0
	v_mov_b32_e32 v247, 0
	v_mov_b32_e32 v248, 0
	v_mov_b32_e32 v249, 0
	v_mov_b32_e32 v68, 0
	v_mov_b32_e32 v69, 0
	v_mov_b32_e32 v70, 0
	v_mov_b32_e32 v71, 0
.Lcf_next6:
	s_add_i32 s1, s4, 56
	s_cmp_gt_i32 s1, 61
	s_cbranch_scc1 .Lcf_lddone
	s_cmp_gt_i32 s1, s9
	s_cbranch_scc0 .Lcf_zero7
	s_add_i32 s10, s8, s1
	s_mul_i32 s10, s10, s86
	s_add_u32 s20, s18, s10
	s_addc_u32 s21, s19, 0
	s_add_u32 s20, s20, 0x6900600
	s_addc_u32 s21, s21, 0
	global_load_dwordx4 v[72:75], v120, s[20:21]
	global_load_dwordx4 v[76:79], v120, s[20:21] offset:1024
	s_branch .Lcf_next7

; #define LAS __attribute__((address_space(3)))
; __device__ __forceinline__ float sigmoidf_(float x) { return __builtin_amdgcn_rcpf(1.0f + __builtin_amdgcn_exp2f(-x * LOG2E)); }
; __device__ __forceinline__ void conv_unit(const Ctx& C0, const Params& p, int l, int unit) {
;     ...
;             if (s >= 0) { const bf16* row = P + (size_t)(t0 - 30 + r) * PN + C_UB + cg8; const v4u a = *(const v4u*)row, g = *(const v4u*)(row + 512);
;                 u0[0] = bflo(a.x) * sigmoidf_(bflo(g.x)); u0[1] = bfhi(a.x) * sigmoidf_(bfhi(g.x)); u0[2] = bflo(a.y) * sigmoidf_(bflo(g.y)); u0[3] = bfhi(a.y) * sigmoidf_(bfhi(g.y));
;                 u1[0] = bflo(a.z) * sigmoidf_(bflo(g.z)); u1[1] = bfhi(a.z) * sigmoidf_(bfhi(g.z)); u1[2] = bflo(a.w) * sigmoidf_(bflo(g.w)); u1[3] = bfhi(a.w) * sigmoidf_(bfhi(g.w)); }
;             *(LAS f32x4*)(U + r * 512 + cg8) = u0; *(LAS f32x4*)(U + r * 512 + cg8 + 4) = u1;
.Lcf_next7:
.Lcf_lddone:
	s_waitcnt vmcnt(0)
	v_lshlrev_b32_e32 v162, 16, v202
	v_and_b32_e32 v163, 0xffff0000, v202
	v_lshlrev_b32_e32 v104, 16, v198
	v_and_b32_e32 v105, 0xffff0000, v198
	v_lshlrev_b32_e32 v164, 16, v203
	v_and_b32_e32 v165, 0xffff0000, v203
	v_lshlrev_b32_e32 v106, 16, v199
	v_and_b32_e32 v107, 0xffff0000, v199
	v_lshlrev_b32_e32 v166, 16, v204
	v_and_b32_e32 v167, 0xffff0000, v204
	v_lshlrev_b32_e32 v108, 16, v200
	v_and_b32_e32 v109, 0xffff0000, v200
	v_lshlrev_b32_e32 v168, 16, v205
	v_and_b32_e32 v169, 0xffff0000, v205
	v_lshlrev_b32_e32 v110, 16, v201
	v_and_b32_e32 v111, 0xffff0000, v201
	v_mul_f32_e32 v162, 0xbfb8aa3b, v162
	v_mul_f32_e32 v163, 0xbfb8aa3b, v163
	v_mul_f32_e32 v164, 0xbfb8aa3b, v164
	v_mul_f32_e32 v165, 0xbfb8aa3b, v165
	v_mul_f32_e32 v166, 0xbfb8aa3b, v166
	v_mul_f32_e32 v167, 0xbfb8aa3b, v167
	v_mul_f32_e32 v168, 0xbfb8aa3b, v168
	v_mul_f32_e32 v169, 0xbfb8aa3b, v169
	v_exp_f32_e32 v162, v162
	v_exp_f32_e32 v163, v163
	v_exp_f32_e32 v164, v164
	v_exp_f32_e32 v165, v165
	v_exp_f32_e32 v166, v166
	v_exp_f32_e32 v167, v167
	v_exp_f32_e32 v168, v168
	v_exp_f32_e32 v169, v169
	v_add_f32_e32 v162, 1.0, v162
	v_add_f32_e32 v163, 1.0, v163
	v_add_f32_e32 v164, 1.0, v164
	v_add_f32_e32 v165, 1.0, v165
	v_add_f32_e32 v166, 1.0, v166
	v_add_f32_e32 v167, 1.0, v167
	v_add_f32_e32 v168, 1.0, v168
	v_add_f32_e32 v169, 1.0, v169
	v_rcp_f32_e32 v162, v162
	v_rcp_f32_e32 v163, v163
	v_rcp_f32_e32 v164, v164
	v_rcp_f32_e32 v165, v165
	v_rcp_f32_e32 v166, v166
	v_rcp_f32_e32 v167, v167
	v_rcp_f32_e32 v168, v168
	v_rcp_f32_e32 v169, v169
	v_pk_mul_f32 v[104:105], v[104:105], v[162:163]
	v_pk_mul_f32 v[106:107], v[106:107], v[164:165]
	v_pk_mul_f32 v[108:109], v[108:109], v[166:167]
	v_pk_mul_f32 v[110:111], v[110:111], v[168:169]
	ds_write_b128 v121, v[104:107]
	ds_write_b128 v121, v[108:111] offset:16
	v_lshlrev_b32_e32 v162, 16, v210
	v_and_b32_e32 v163, 0xffff0000, v210
	v_lshlrev_b32_e32 v112, 16, v206
	v_and_b32_e32 v113, 0xffff0000, v206
	v_lshlrev_b32_e32 v164, 16, v211
	v_and_b32_e32 v165, 0xffff0000, v211
	v_lshlrev_b32_e32 v114, 16, v207
	v_and_b32_e32 v115, 0xffff0000, v207
	v_lshlrev_b32_e32 v166, 16, v212
	v_and_b32_e32 v167, 0xffff0000, v212
	v_lshlrev_b32_e32 v116, 16, v208
	v_and_b32_e32 v117, 0xffff0000, v208
	v_lshlrev_b32_e32 v168, 16, v213
	v_and_b32_e32 v169, 0xffff0000, v213
	v_lshlrev_b32_e32 v118, 16, v209
	v_and_b32_e32 v119, 0xffff0000, v209
	v_mul_f32_e32 v162, 0xbfb8aa3b, v162
	v_mul_f32_e32 v163, 0xbfb8aa3b, v163
	v_mul_f32_e32 v164, 0xbfb8aa3b, v164
	v_mul_f32_e32 v165, 0xbfb8aa3b, v165
	v_mul_f32_e32 v166, 0xbfb8aa3b, v166
	v_mul_f32_e32 v167, 0xbfb8aa3b, v167
	v_mul_f32_e32 v168, 0xbfb8aa3b, v168
	v_mul_f32_e32 v169, 0xbfb8aa3b, v169
	v_exp_f32_e32 v162, v162
	v_exp_f32_e32 v163, v163
	v_exp_f32_e32 v164, v164
	v_exp_f32_e32 v165, v165
	v_exp_f32_e32 v166, v166
	v_exp_f32_e32 v167, v167
	v_exp_f32_e32 v168, v168
	v_exp_f32_e32 v169, v169
	v_add_f32_e32 v162, 1.0, v162
	v_add_f32_e32 v163, 1.0, v163
	v_add_f32_e32 v164, 1.0, v164
	v_add_f32_e32 v165, 1.0, v165
	v_add_f32_e32 v166, 1.0, v166
	v_add_f32_e32 v167, 1.0, v167
	v_add_f32_e32 v168, 1.0, v168
	v_add_f32_e32 v169, 1.0, v169
	v_rcp_f32_e32 v162, v162
	v_rcp_f32_e32 v163, v163
	v_rcp_f32_e32 v164, v164
	v_rcp_f32_e32 v165, v165
	v_rcp_f32_e32 v166, v166
	v_rcp_f32_e32 v167, v167
	v_rcp_f32_e32 v168, v168
	v_rcp_f32_e32 v169, v169
	v_pk_mul_f32 v[112:113], v[112:113], v[162:163]
	v_pk_mul_f32 v[114:115], v[114:115], v[164:165]
	v_pk_mul_f32 v[116:117], v[116:117], v[166:167]
	v_pk_mul_f32 v[118:119], v[118:119], v[168:169]
	ds_write_b128 v121, v[112:115] offset:16384
	ds_write_b128 v121, v[116:119] offset:16400
	v_lshlrev_b32_e32 v162, 16, v218
	v_and_b32_e32 v163, 0xffff0000, v218
	v_lshlrev_b32_e32 v104, 16, v214
	v_and_b32_e32 v105, 0xffff0000, v214
	v_lshlrev_b32_e32 v164, 16, v219
	v_and_b32_e32 v165, 0xffff0000, v219
	v_lshlrev_b32_e32 v106, 16, v215
	v_and_b32_e32 v107, 0xffff0000, v215
	v_lshlrev_b32_e32 v166, 16, v220
	v_and_b32_e32 v167, 0xffff0000, v220
	v_lshlrev_b32_e32 v108, 16, v216
	v_and_b32_e32 v109, 0xffff0000, v216
	v_lshlrev_b32_e32 v168, 16, v221
	v_and_b32_e32 v169, 0xffff0000, v221
	v_lshlrev_b32_e32 v110, 16, v217
	v_and_b32_e32 v111, 0xffff0000, v217
	v_mul_f32_e32 v162, 0xbfb8aa3b, v162
	v_mul_f32_e32 v163, 0xbfb8aa3b, v163
	v_mul_f32_e32 v164, 0xbfb8aa3b, v164
	v_mul_f32_e32 v165, 0xbfb8aa3b, v165
	v_mul_f32_e32 v166, 0xbfb8aa3b, v166
	v_mul_f32_e32 v167, 0xbfb8aa3b, v167
	v_mul_f32_e32 v168, 0xbfb8aa3b, v168
	v_mul_f32_e32 v169, 0xbfb8aa3b, v169
	v_exp_f32_e32 v162, v162
	v_exp_f32_e32 v163, v163
	v_exp_f32_e32 v164, v164
	v_exp_f32_e32 v165, v165
	v_exp_f32_e32 v166, v166
	v_exp_f32_e32 v167, v167
	v_exp_f32_e32 v168, v168
	v_exp_f32_e32 v169, v169
	v_add_f32_e32 v162, 1.0, v162
	v_add_f32_e32 v163, 1.0, v163
	v_add_f32_e32 v164, 1.0, v164
	v_add_f32_e32 v165, 1.0, v165
	v_add_f32_e32 v166, 1.0, v166
	v_add_f32_e32 v167, 1.0, v167
	v_add_f32_e32 v168, 1.0, v168
	v_add_f32_e32 v169, 1.0, v169
	v_rcp_f32_e32 v162, v162
	v_rcp_f32_e32 v163, v163
	v_rcp_f32_e32 v164, v164
	v_rcp_f32_e32 v165, v165
	v_rcp_f32_e32 v166, v166
	v_rcp_f32_e32 v167, v167
	v_rcp_f32_e32 v168, v168
	v_rcp_f32_e32 v169, v169
	v_pk_mul_f32 v[104:105], v[104:105], v[162:163]
	v_pk_mul_f32 v[106:107], v[106:107], v[164:165]
	v_pk_mul_f32 v[108:109], v[108:109], v[166:167]
	v_pk_mul_f32 v[110:111], v[110:111], v[168:169]
	ds_write_b128 v121, v[104:107] offset:32768
	ds_write_b128 v121, v[108:111] offset:32784
	v_lshlrev_b32_e32 v162, 16, v226
	v_and_b32_e32 v163, 0xffff0000, v226
	v_lshlrev_b32_e32 v112, 16, v222
; #define LAS __attribute__((address_space(3)))
; __device__ __forceinline__ float sigmoidf_(float x) { return __builtin_amdgcn_rcpf(1.0f + __builtin_amdgcn_exp2f(-x * LOG2E)); }
; __device__ __forceinline__ void conv_unit(const Ctx& C0, const Params& p, int l, int unit) {
;     ...
;             if (s >= 0) { const bf16* row = P + (size_t)(t0 - 30 + r) * PN + C_UB + cg8; const v4u a = *(const v4u*)row, g = *(const v4u*)(row + 512);
;                 u0[0] = bflo(a.x) * sigmoidf_(bflo(g.x)); u0[1] = bfhi(a.x) * sigmoidf_(bfhi(g.x)); u0[2] = bflo(a.y) * sigmoidf_(bflo(g.y)); u0[3] = bfhi(a.y) * sigmoidf_(bfhi(g.y));
;                 u1[0] = bflo(a.z) * sigmoidf_(bflo(g.z)); u1[1] = bfhi(a.z) * sigmoidf_(bfhi(g.z)); u1[2] = bflo(a.w) * sigmoidf_(bflo(g.w)); u1[3] = bfhi(a.w) * sigmoidf_(bfhi(g.w)); }
;             *(LAS f32x4*)(U + r * 512 + cg8) = u0; *(LAS f32x4*)(U + r * 512 + cg8 + 4) = u1;
	v_and_b32_e32 v113, 0xffff0000, v222
	v_lshlrev_b32_e32 v164, 16, v227
	v_and_b32_e32 v165, 0xffff0000, v227
	v_lshlrev_b32_e32 v114, 16, v223
	v_and_b32_e32 v115, 0xffff0000, v223
	v_lshlrev_b32_e32 v166, 16, v228
	v_and_b32_e32 v167, 0xffff0000, v228
	v_lshlrev_b32_e32 v116, 16, v224
	v_and_b32_e32 v117, 0xffff0000, v224
	v_lshlrev_b32_e32 v168, 16, v229
	v_and_b32_e32 v169, 0xffff0000, v229
	v_lshlrev_b32_e32 v118, 16, v225
	v_and_b32_e32 v119, 0xffff0000, v225
	v_mul_f32_e32 v162, 0xbfb8aa3b, v162
	v_mul_f32_e32 v163, 0xbfb8aa3b, v163
	v_mul_f32_e32 v164, 0xbfb8aa3b, v164
	v_mul_f32_e32 v165, 0xbfb8aa3b, v165
	v_mul_f32_e32 v166, 0xbfb8aa3b, v166
	v_mul_f32_e32 v167, 0xbfb8aa3b, v167
	v_mul_f32_e32 v168, 0xbfb8aa3b, v168
	v_mul_f32_e32 v169, 0xbfb8aa3b, v169
	v_exp_f32_e32 v162, v162
	v_exp_f32_e32 v163, v163
	v_exp_f32_e32 v164, v164
	v_exp_f32_e32 v165, v165
	v_exp_f32_e32 v166, v166
	v_exp_f32_e32 v167, v167
	v_exp_f32_e32 v168, v168
	v_exp_f32_e32 v169, v169
	v_add_f32_e32 v162, 1.0, v162
	v_add_f32_e32 v163, 1.0, v163
	v_add_f32_e32 v164, 1.0, v164
	v_add_f32_e32 v165, 1.0, v165
	v_add_f32_e32 v166, 1.0, v166
	v_add_f32_e32 v167, 1.0, v167
	v_add_f32_e32 v168, 1.0, v168
	v_add_f32_e32 v169, 1.0, v169
	v_rcp_f32_e32 v162, v162
	v_rcp_f32_e32 v163, v163
	v_rcp_f32_e32 v164, v164
	v_rcp_f32_e32 v165, v165
	v_rcp_f32_e32 v166, v166
	v_rcp_f32_e32 v167, v167
	v_rcp_f32_e32 v168, v168
	v_rcp_f32_e32 v169, v169
	v_pk_mul_f32 v[112:113], v[112:113], v[162:163]
	v_pk_mul_f32 v[114:115], v[114:115], v[164:165]
	v_pk_mul_f32 v[116:117], v[116:117], v[166:167]
	v_pk_mul_f32 v[118:119], v[118:119], v[168:169]
	ds_write_b128 v121, v[112:115] offset:49152
	ds_write_b128 v121, v[116:119] offset:49168
	v_lshlrev_b32_e32 v162, 16, v234
	v_and_b32_e32 v163, 0xffff0000, v234
	v_lshlrev_b32_e32 v104, 16, v230
	v_and_b32_e32 v105, 0xffff0000, v230
	v_lshlrev_b32_e32 v164, 16, v235
	v_and_b32_e32 v165, 0xffff0000, v235
	v_lshlrev_b32_e32 v106, 16, v231
	v_and_b32_e32 v107, 0xffff0000, v231
	v_lshlrev_b32_e32 v166, 16, v236
	v_and_b32_e32 v167, 0xffff0000, v236
	v_lshlrev_b32_e32 v108, 16, v232
	v_and_b32_e32 v109, 0xffff0000, v232
	v_lshlrev_b32_e32 v168, 16, v237
	v_and_b32_e32 v169, 0xffff0000, v237
	v_lshlrev_b32_e32 v110, 16, v233
	v_and_b32_e32 v111, 0xffff0000, v233
	v_mul_f32_e32 v162, 0xbfb8aa3b, v162
	v_mul_f32_e32 v163, 0xbfb8aa3b, v163
	v_mul_f32_e32 v164, 0xbfb8aa3b, v164
	v_mul_f32_e32 v165, 0xbfb8aa3b, v165
	v_mul_f32_e32 v166, 0xbfb8aa3b, v166
	v_mul_f32_e32 v167, 0xbfb8aa3b, v167
	v_mul_f32_e32 v168, 0xbfb8aa3b, v168
	v_mul_f32_e32 v169, 0xbfb8aa3b, v169
	v_exp_f32_e32 v162, v162
	v_exp_f32_e32 v163, v163
	v_exp_f32_e32 v164, v164
	v_exp_f32_e32 v165, v165
	v_exp_f32_e32 v166, v166
	v_exp_f32_e32 v167, v167
	v_exp_f32_e32 v168, v168
	v_exp_f32_e32 v169, v169
	v_add_f32_e32 v162, 1.0, v162
	v_add_f32_e32 v163, 1.0, v163
	v_add_f32_e32 v164, 1.0, v164
	v_add_f32_e32 v165, 1.0, v165
	v_add_f32_e32 v166, 1.0, v166
	v_add_f32_e32 v167, 1.0, v167
	v_add_f32_e32 v168, 1.0, v168
	v_add_f32_e32 v169, 1.0, v169
	v_rcp_f32_e32 v162, v162
	v_rcp_f32_e32 v163, v163
	v_rcp_f32_e32 v164, v164
	v_rcp_f32_e32 v165, v165
	v_rcp_f32_e32 v166, v166
	v_rcp_f32_e32 v167, v167
	v_rcp_f32_e32 v168, v168
	v_rcp_f32_e32 v169, v169
	v_pk_mul_f32 v[104:105], v[104:105], v[162:163]
	v_pk_mul_f32 v[106:107], v[106:107], v[164:165]
	v_pk_mul_f32 v[108:109], v[108:109], v[166:167]
	v_pk_mul_f32 v[110:111], v[110:111], v[168:169]
	ds_write_b128 v122, v[104:107]
	ds_write_b128 v122, v[108:111] offset:16
	v_lshlrev_b32_e32 v162, 16, v242
	v_and_b32_e32 v163, 0xffff0000, v242
	v_lshlrev_b32_e32 v112, 16, v238
	v_and_b32_e32 v113, 0xffff0000, v238
	v_lshlrev_b32_e32 v164, 16, v243
	v_and_b32_e32 v165, 0xffff0000, v243
	v_lshlrev_b32_e32 v114, 16, v239
	v_and_b32_e32 v115, 0xffff0000, v239
	v_lshlrev_b32_e32 v166, 16, v244
	v_and_b32_e32 v167, 0xffff0000, v244
	v_lshlrev_b32_e32 v116, 16, v240
	v_and_b32_e32 v117, 0xffff0000, v240
	v_lshlrev_b32_e32 v168, 16, v245
	v_and_b32_e32 v169, 0xffff0000, v245
	v_lshlrev_b32_e32 v118, 16, v241
	v_and_b32_e32 v119, 0xffff0000, v241
	v_mul_f32_e32 v162, 0xbfb8aa3b, v162
	v_mul_f32_e32 v163, 0xbfb8aa3b, v163
	v_mul_f32_e32 v164, 0xbfb8aa3b, v164
	v_mul_f32_e32 v165, 0xbfb8aa3b, v165
	v_mul_f32_e32 v166, 0xbfb8aa3b, v166
	v_mul_f32_e32 v167, 0xbfb8aa3b, v167
	v_mul_f32_e32 v168, 0xbfb8aa3b, v168
	v_mul_f32_e32 v169, 0xbfb8aa3b, v169
	v_exp_f32_e32 v162, v162
	v_exp_f32_e32 v163, v163
	v_exp_f32_e32 v164, v164
	v_exp_f32_e32 v165, v165
	v_exp_f32_e32 v166, v166
	v_exp_f32_e32 v167, v167
	v_exp_f32_e32 v168, v168
	v_exp_f32_e32 v169, v169
	v_add_f32_e32 v162, 1.0, v162
	v_add_f32_e32 v163, 1.0, v163
	v_add_f32_e32 v164, 1.0, v164
	v_add_f32_e32 v165, 1.0, v165
	v_add_f32_e32 v166, 1.0, v166
	v_add_f32_e32 v167, 1.0, v167
	v_add_f32_e32 v168, 1.0, v168
	v_add_f32_e32 v169, 1.0, v169
	v_rcp_f32_e32 v162, v162
	v_rcp_f32_e32 v163, v163
	v_rcp_f32_e32 v164, v164
	v_rcp_f32_e32 v165, v165
	v_rcp_f32_e32 v166, v166
	v_rcp_f32_e32 v167, v167
	v_rcp_f32_e32 v168, v168
	v_rcp_f32_e32 v169, v169
	v_pk_mul_f32 v[112:113], v[112:113], v[162:163]
	v_pk_mul_f32 v[114:115], v[114:115], v[164:165]
	v_pk_mul_f32 v[116:117], v[116:117], v[166:167]
	v_pk_mul_f32 v[118:119], v[118:119], v[168:169]
	ds_write_b128 v122, v[112:115] offset:16384
	ds_write_b128 v122, v[116:119] offset:16400
	v_lshlrev_b32_e32 v162, 16, v68
	v_and_b32_e32 v163, 0xffff0000, v68
	v_lshlrev_b32_e32 v104, 16, v246
	v_and_b32_e32 v105, 0xffff0000, v246
; #define LAS __attribute__((address_space(3)))
; __device__ __forceinline__ void conv_unit(const Ctx& C0, const Params& p, int l, int unit) {
;     ...
;             *(LAS f32x4*)(U + r * 512 + cg8) = u0; *(LAS f32x4*)(U + r * 512 + cg8 + 4) = u1;
;         }
;       }
;     }
;     __syncthreads();
;     float w[31];
; #pragma unroll
;     for (int j = 0; j < 31; ++j) w[j] = p.w_dw[(size_t)l * 31 * 512 + j * 512 + c];
;     const float bias = p.b_dw[l * 512 + c];
	v_lshlrev_b32_e32 v164, 16, v69
	v_and_b32_e32 v165, 0xffff0000, v69
	v_lshlrev_b32_e32 v106, 16, v247
	v_and_b32_e32 v107, 0xffff0000, v247
	v_lshlrev_b32_e32 v166, 16, v70
	v_and_b32_e32 v167, 0xffff0000, v70
	v_lshlrev_b32_e32 v108, 16, v248
	v_and_b32_e32 v109, 0xffff0000, v248
	v_lshlrev_b32_e32 v168, 16, v71
	v_and_b32_e32 v169, 0xffff0000, v71
	v_lshlrev_b32_e32 v110, 16, v249
	v_and_b32_e32 v111, 0xffff0000, v249
	v_mul_f32_e32 v162, 0xbfb8aa3b, v162
	v_mul_f32_e32 v163, 0xbfb8aa3b, v163
	v_mul_f32_e32 v164, 0xbfb8aa3b, v164
	v_mul_f32_e32 v165, 0xbfb8aa3b, v165
	v_mul_f32_e32 v166, 0xbfb8aa3b, v166
	v_mul_f32_e32 v167, 0xbfb8aa3b, v167
	v_mul_f32_e32 v168, 0xbfb8aa3b, v168
	v_mul_f32_e32 v169, 0xbfb8aa3b, v169
	v_exp_f32_e32 v162, v162
	v_exp_f32_e32 v163, v163
	v_exp_f32_e32 v164, v164
	v_exp_f32_e32 v165, v165
	v_exp_f32_e32 v166, v166
	v_exp_f32_e32 v167, v167
	v_exp_f32_e32 v168, v168
	v_exp_f32_e32 v169, v169
	v_add_f32_e32 v162, 1.0, v162
	v_add_f32_e32 v163, 1.0, v163
	v_add_f32_e32 v164, 1.0, v164
	v_add_f32_e32 v165, 1.0, v165
	v_add_f32_e32 v166, 1.0, v166
	v_add_f32_e32 v167, 1.0, v167
	v_add_f32_e32 v168, 1.0, v168
	v_add_f32_e32 v169, 1.0, v169
	v_rcp_f32_e32 v162, v162
	v_rcp_f32_e32 v163, v163
	v_rcp_f32_e32 v164, v164
	v_rcp_f32_e32 v165, v165
	v_rcp_f32_e32 v166, v166
	v_rcp_f32_e32 v167, v167
	v_rcp_f32_e32 v168, v168
	v_rcp_f32_e32 v169, v169
	v_pk_mul_f32 v[104:105], v[104:105], v[162:163]
	v_pk_mul_f32 v[106:107], v[106:107], v[164:165]
	v_pk_mul_f32 v[108:109], v[108:109], v[166:167]
	v_pk_mul_f32 v[110:111], v[110:111], v[168:169]
	ds_write_b128 v122, v[104:107] offset:32768
	ds_write_b128 v122, v[108:111] offset:32784
	s_add_i32 s1, s4, 56
	s_cmp_gt_i32 s1, 61
	s_cbranch_scc1 .Lcf_done
	v_lshlrev_b32_e32 v162, 16, v76
	v_and_b32_e32 v163, 0xffff0000, v76
	v_lshlrev_b32_e32 v112, 16, v72
	v_and_b32_e32 v113, 0xffff0000, v72
	v_lshlrev_b32_e32 v164, 16, v77
	v_and_b32_e32 v165, 0xffff0000, v77
	v_lshlrev_b32_e32 v114, 16, v73
	v_and_b32_e32 v115, 0xffff0000, v73
	v_lshlrev_b32_e32 v166, 16, v78
	v_and_b32_e32 v167, 0xffff0000, v78
	v_lshlrev_b32_e32 v116, 16, v74
	v_and_b32_e32 v117, 0xffff0000, v74
	v_lshlrev_b32_e32 v168, 16, v79
	v_and_b32_e32 v169, 0xffff0000, v79
	v_lshlrev_b32_e32 v118, 16, v75
	v_and_b32_e32 v119, 0xffff0000, v75
	v_mul_f32_e32 v162, 0xbfb8aa3b, v162
	v_mul_f32_e32 v163, 0xbfb8aa3b, v163
	v_mul_f32_e32 v164, 0xbfb8aa3b, v164
	v_mul_f32_e32 v165, 0xbfb8aa3b, v165
	v_mul_f32_e32 v166, 0xbfb8aa3b, v166
	v_mul_f32_e32 v167, 0xbfb8aa3b, v167
	v_mul_f32_e32 v168, 0xbfb8aa3b, v168
	v_mul_f32_e32 v169, 0xbfb8aa3b, v169
	v_exp_f32_e32 v162, v162
	v_exp_f32_e32 v163, v163
	v_exp_f32_e32 v164, v164
	v_exp_f32_e32 v165, v165
	v_exp_f32_e32 v166, v166
	v_exp_f32_e32 v167, v167
	v_exp_f32_e32 v168, v168
	v_exp_f32_e32 v169, v169
	v_add_f32_e32 v162, 1.0, v162
	v_add_f32_e32 v163, 1.0, v163
	v_add_f32_e32 v164, 1.0, v164
	v_add_f32_e32 v165, 1.0, v165
	v_add_f32_e32 v166, 1.0, v166
	v_add_f32_e32 v167, 1.0, v167
	v_add_f32_e32 v168, 1.0, v168
	v_add_f32_e32 v169, 1.0, v169
	v_rcp_f32_e32 v162, v162
	v_rcp_f32_e32 v163, v163
	v_rcp_f32_e32 v164, v164
	v_rcp_f32_e32 v165, v165
	v_rcp_f32_e32 v166, v166
	v_rcp_f32_e32 v167, v167
	v_rcp_f32_e32 v168, v168
	v_rcp_f32_e32 v169, v169
	v_pk_mul_f32 v[112:113], v[112:113], v[162:163]
	v_pk_mul_f32 v[114:115], v[114:115], v[164:165]
	v_pk_mul_f32 v[116:117], v[116:117], v[166:167]
	v_pk_mul_f32 v[118:119], v[118:119], v[168:169]
	ds_write_b128 v122, v[112:115] offset:49152
	ds_write_b128 v122, v[116:119] offset:49168
.Lcf_done:
	s_waitcnt lgkmcnt(0)
	s_barrier
	v_lshl_add_u32 v0, v10, 2, 0
	s_mov_b32 s0, 0
	s_mov_b32 s1, 8
	s_mov_b32 s8, 4
	v_readlane_b32 s45, v251, 13
	v_readlane_b32 s46, v251, 14
	v_readlane_b32 s47, v251, 15
	v_readlane_b32 s48, v251, 16
	v_readlane_b32 s49, v251, 17
	v_readlane_b32 s50, v251, 18
	v_readlane_b32 s51, v251, 19
	v_readlane_b32 s54, v251, 22
	v_readlane_b32 s55, v251, 23
	v_readlane_b32 s56, v251, 24
	v_readlane_b32 s57, v251, 25
	v_readlane_b32 s58, v251, 26
	v_readlane_b32 s59, v251, 27
	s_waitcnt vmcnt(31)
	v_mov_b32_e32 v3, v2
	s_waitcnt vmcnt(30)
	v_mov_b32_e32 v5, v4
	s_waitcnt vmcnt(29)
	v_mov_b32_e32 v7, v6
	s_waitcnt vmcnt(28)
	v_mov_b32_e32 v9, v8
	s_waitcnt vmcnt(27)
	v_mov_b32_e32 v13, v12
	s_waitcnt vmcnt(26)
	v_mov_b32_e32 v15, v14
	s_waitcnt vmcnt(25)
	v_mov_b32_e32 v17, v16
	s_waitcnt vmcnt(24)
	v_mov_b32_e32 v19, v18
	s_waitcnt vmcnt(23)
	v_mov_b32_e32 v21, v20
	s_waitcnt vmcnt(22)
	v_mov_b32_e32 v23, v22
	s_waitcnt vmcnt(21)
	v_mov_b32_e32 v25, v24
	s_waitcnt vmcnt(20)
	v_mov_b32_e32 v27, v26
	s_waitcnt vmcnt(19)
	v_mov_b32_e32 v29, v28
	s_waitcnt vmcnt(18)
	v_mov_b32_e32 v31, v30
	s_waitcnt vmcnt(17)
	v_mov_b32_e32 v33, v32
	s_waitcnt vmcnt(16)
	v_mov_b32_e32 v35, v34
	s_waitcnt vmcnt(15)
	v_mov_b32_e32 v37, v36
	s_waitcnt vmcnt(14)
	v_mov_b32_e32 v39, v38
	s_waitcnt vmcnt(13)
	v_mov_b32_e32 v41, v40
	s_waitcnt vmcnt(12)
	v_mov_b32_e32 v43, v42
	s_waitcnt vmcnt(11)
	v_mov_b32_e32 v45, v44
	s_waitcnt vmcnt(10)
	v_mov_b32_e32 v47, v46
	s_waitcnt vmcnt(9)
	v_mov_b32_e32 v49, v48
	s_waitcnt vmcnt(8)
	v_mov_b32_e32 v51, v50
	s_waitcnt vmcnt(7)
	v_mov_b32_e32 v53, v52
	s_waitcnt vmcnt(6)
	v_mov_b32_e32 v55, v54
	s_waitcnt vmcnt(5)
	v_mov_b32_e32 v57, v56
	s_waitcnt vmcnt(4)
	v_mov_b32_e32 v59, v58
	s_waitcnt vmcnt(3)
	v_mov_b32_e32 v61, v60
	s_waitcnt vmcnt(2)
	v_mov_b32_e32 v63, v62
	s_waitcnt vmcnt(1)
	v_mov_b32_e32 v65, v64
	s_waitcnt vmcnt(0)
	v_mov_b32_e32 v67, v66
